# attention: second-half K/V global loads interleaved with cvt_pk as well (skip path moved to stub)
# baseline (speedup 1.0000x reference)
; #define SBAR() __builtin_amdgcn_sched_barrier(0)
; #define SLOAD(i, k0) do { sr_[i].vs0 = St::ld8(&Vh[(long)((k0) + sr) * LDK + sc]); sr_[i].vs1 = St::ld8(&Vh[(long)((k0) + 32 + sr) * LDK + sc]); \
;     sr_[i].ks0 = St::ld8(&Kh[(long)((k0) + sr) * LDK + sc]); sr_[i].ks1 = St::ld8(&Kh[(long)((k0) + 32 + sr) * LDK + sc]); } while (0)
; #define RESC(a) do { if (__any((a) < 1.f)) { if (hi == 0) al_l[r32] = (a); asm volatile("s_waitcnt lgkmcnt(0)" ::: "memory"); \
;     for (int d = 0; d < 4; ++d) for (int r = 0; r < 16; ++r) o[d][r] *= al_l[crow(r, hi)]; } } while (0)
; __device__ __forceinline__ void partialSM(f32x16& p0, f32x16& p1, float& m_reg, float& mn, float& alpha) {
;     ...
;   float mnC = -mn * C;
;   for (int r = 0; r < 16; ++r) p0[r] = fmaf(p0[r], C, mnC); for (int r = 0; r < 16; ++r) p1[r] = fmaf(p1[r], C, mnC);
;   for (int r = 0; r < 16; ++r) p0[r] = __builtin_amdgcn_exp2f(p0[r]);
; }
; __device__ __forceinline__ void finishSM(f32x16& p0, f32x16& p1, float alpha, float& l_reg, bf16x8& pa0, bf16x8& pa1, bf16x8& pa2, bf16x8& pa3) {
;   for (int r = 0; r < 16; ++r) p1[r] = __builtin_amdgcn_exp2f(p1[r]);
;   float ps = 0; for (int r = 0; r < 16; ++r) ps += p0[r]; for (int r = 0; r < 16; ++r) ps += p1[r];
;   { auto rr = __builtin_amdgcn_permlane32_swap(__float_as_uint(ps), __float_as_uint(ps), false, false);
;     ps = __uint_as_float(rr[0]) + __uint_as_float(rr[1]); }
;   l_reg = l_reg * alpha + ps;
;     ...
;   PK4(p0, 0, pa0); PK4(p0, 8, pa1); PK4(p1, 0, pa2); PK4(p1, 8, pa3);
; template <typename TQ>
; __device__ __forceinline__ void attn_dense_body(const TQ* __restrict__ Qb, const bf16* __restrict__ Kh, const bf16* __restrict__ Vh,
;                                                 unsigned short* __restrict__ Ob, int seq, char* lds, const int wave_s) {
;     ...
;     RESC(alB); __syncthreads();
;     SBAR(); qkt(pA0, pA1, K_lds, qr, r32, hi);
;     finishSM(pB0, pB1, alB, l_reg, pa0, pa1, pa2, pa3); SBAR();
;     if (SDEPTH == 1 || j + 3 < NT) SLOAD(SE, (j + 1 + SDEPTH) * KVBLK); SBAR();
.LBB0_579:
	v_xor_b32_e32 v189, 0x18000, v189
	v_xor_b32_e32 v199, 0x18000, v199
	v_xor_b32_e32 v192, 0x18000, v192
	v_xor_b32_e32 v191, 0x18000, v191
	v_mul_f32_e32 v207, 0xbe0293ee, v206
	v_fmamk_f32 v80, v80, 0x3e0293ee, v207
	v_fmamk_f32 v81, v81, 0x3e0293ee, v207
	v_fmamk_f32 v82, v82, 0x3e0293ee, v207
	v_fmamk_f32 v83, v83, 0x3e0293ee, v207
	v_fmamk_f32 v84, v84, 0x3e0293ee, v207
	v_fmamk_f32 v85, v85, 0x3e0293ee, v207
	v_fmamk_f32 v86, v86, 0x3e0293ee, v207
	v_fmamk_f32 v87, v87, 0x3e0293ee, v207
	v_fmamk_f32 v88, v88, 0x3e0293ee, v207
	v_fmamk_f32 v89, v89, 0x3e0293ee, v207
	v_fmamk_f32 v90, v90, 0x3e0293ee, v207
	v_fmamk_f32 v91, v91, 0x3e0293ee, v207
	v_fmamk_f32 v92, v92, 0x3e0293ee, v207
	v_fmamk_f32 v93, v93, 0x3e0293ee, v207
	v_fmamk_f32 v94, v94, 0x3e0293ee, v207
	v_fmamk_f32 v95, v95, 0x3e0293ee, v207
	v_exp_f32_e32 v160, v80
	v_exp_f32_e32 v175, v81
	v_exp_f32_e32 v161, v82
	v_exp_f32_e32 v174, v83
	v_exp_f32_e32 v162, v84
	v_exp_f32_e32 v173, v85
	v_exp_f32_e32 v163, v86
	v_exp_f32_e32 v172, v87
	v_exp_f32_e32 v164, v88
	v_exp_f32_e32 v171, v89
	v_exp_f32_e32 v165, v90
	v_exp_f32_e32 v170, v91
	v_exp_f32_e32 v166, v92
	v_exp_f32_e32 v169, v93
	v_exp_f32_e32 v167, v94
	v_exp_f32_e32 v168, v95
	v_fmamk_f32 v216, v64, 0x3e0293ee, v207
	v_fmamk_f32 v217, v65, 0x3e0293ee, v207
	v_fmamk_f32 v218, v66, 0x3e0293ee, v207
	v_fmamk_f32 v219, v67, 0x3e0293ee, v207
	v_fmamk_f32 v224, v68, 0x3e0293ee, v207
	v_fmamk_f32 v209, v69, 0x3e0293ee, v207
	v_fmamk_f32 v210, v70, 0x3e0293ee, v207
	v_fmamk_f32 v211, v71, 0x3e0293ee, v207
	v_fmamk_f32 v212, v72, 0x3e0293ee, v207
	v_fmamk_f32 v213, v73, 0x3e0293ee, v207
	v_fmamk_f32 v214, v74, 0x3e0293ee, v207
	v_fmamk_f32 v215, v75, 0x3e0293ee, v207
	v_fmamk_f32 v208, v76, 0x3e0293ee, v207
	v_fmamk_f32 v225, v77, 0x3e0293ee, v207
	v_fmamk_f32 v226, v78, 0x3e0293ee, v207
	v_fmac_f32_e32 v207, 0x3e0293ee, v79
	s_waitcnt lgkmcnt(0)
	s_barrier
	ds_read_b128 v[64:67], v189 offset:32768
	ds_read_b128 v[68:71], v189 offset:40960
	ds_read_b128 v[228:231], v199 offset:32768
	ds_read_b128 v[232:235], v199 offset:40960
	ds_read_b128 v[240:243], v192 offset:32768
	ds_read_b128 v[244:247], v192 offset:40960
	v_exp_f32_e32 v221, v207
	s_waitcnt lgkmcnt(5)
	v_mfma_f32_32x32x16_bf16 v[80:95], v[64:67], v[112:115], 0
	v_add_f32_e32 v207, v175, v160
	v_add_f32_e32 v207, v161, v207
	v_add_f32_e32 v207, v174, v207
	v_add_f32_e32 v207, v162, v207
	v_add_f32_e32 v207, v173, v207
	v_add_f32_e32 v207, v163, v207
	v_add_f32_e32 v207, v172, v207
	s_waitcnt lgkmcnt(4)
	v_mfma_f32_32x32x16_bf16 v[64:79], v[68:71], v[112:115], 0
	v_add_f32_e32 v207, v164, v207
	v_add_f32_e32 v207, v171, v207
	v_add_f32_e32 v207, v165, v207
	v_add_f32_e32 v207, v170, v207
	v_exp_f32_e32 v194, v216
	v_add_f32_e32 v207, v166, v207
	v_exp_f32_e32 v195, v217
	s_waitcnt lgkmcnt(3)
	v_mfma_f32_32x32x16_bf16 v[80:95], v[228:231], v[108:111], v[80:95]
	v_add_f32_e32 v207, v169, v207
	v_exp_f32_e32 v196, v218
	v_add_f32_e32 v207, v167, v207
	v_exp_f32_e32 v197, v219
	v_add_f32_e32 v207, v168, v207
	v_exp_f32_e32 v216, v224
	v_add_f32_e32 v207, v194, v207
	s_waitcnt lgkmcnt(2)
	v_mfma_f32_32x32x16_bf16 v[64:79], v[232:235], v[108:111], v[64:79]
	ds_read_b128 v[228:231], v191 offset:32768
	ds_read_b128 v[232:235], v191 offset:40960
	v_exp_f32_e32 v209, v209
	v_add_f32_e32 v207, v195, v207
	v_exp_f32_e32 v210, v210
	v_add_f32_e32 v207, v196, v207
	v_exp_f32_e32 v211, v211
	v_add_f32_e32 v207, v197, v207
	s_waitcnt lgkmcnt(3)
	v_mfma_f32_32x32x16_bf16 v[80:95], v[240:243], v[120:123], v[80:95]
	v_exp_f32_e32 v212, v212
	v_add_f32_e32 v207, v216, v207
	v_exp_f32_e32 v213, v213
	v_add_f32_e32 v207, v209, v207
	v_exp_f32_e32 v214, v214
	v_add_f32_e32 v207, v210, v207
	v_exp_f32_e32 v215, v215
	s_waitcnt lgkmcnt(2)
	v_mfma_f32_32x32x16_bf16 v[64:79], v[244:247], v[120:123], v[64:79]
	ds_read_b128 v[240:243], v189 offset:32896
	ds_read_b128 v[244:247], v189 offset:41088
	v_add_f32_e32 v207, v211, v207
	v_exp_f32_e32 v217, v208
	v_add_f32_e32 v207, v212, v207
	v_exp_f32_e32 v218, v225
	v_add_f32_e32 v207, v213, v207
	v_exp_f32_e32 v219, v226
	s_waitcnt lgkmcnt(3)
	v_mfma_f32_32x32x16_bf16 v[80:95], v[228:231], v[124:127], v[80:95]
	v_add_f32_e32 v207, v214, v207
	v_add_f32_e32 v207, v215, v207
	v_add_f32_e32 v207, v217, v207
	v_add_f32_e32 v207, v218, v207
	v_add_f32_e32 v207, v219, v207
	v_add_f32_e32 v207, v221, v207
	s_waitcnt lgkmcnt(2)
	v_mfma_f32_32x32x16_bf16 v[64:79], v[232:235], v[124:127], v[64:79]
	ds_read_b128 v[228:231], v199 offset:32896
	ds_read_b128 v[232:235], v199 offset:41088
	s_waitcnt lgkmcnt(3)
	v_mfma_f32_32x32x16_bf16 v[80:95], v[240:243], v[116:119], v[80:95]
	s_waitcnt lgkmcnt(2)
	v_mfma_f32_32x32x16_bf16 v[64:79], v[244:247], v[116:119], v[64:79]
	ds_read_b128 v[240:243], v192 offset:32896
	ds_read_b128 v[244:247], v192 offset:41088
	s_waitcnt lgkmcnt(3)
	v_mfma_f32_32x32x16_bf16 v[80:95], v[228:231], v[104:107], v[80:95]
	s_waitcnt lgkmcnt(2)
	v_mfma_f32_32x32x16_bf16 v[64:79], v[232:235], v[104:107], v[64:79]
	ds_read_b128 v[228:231], v191 offset:32896
	ds_read_b128 v[232:235], v191 offset:41088
	s_waitcnt lgkmcnt(3)
	v_mfma_f32_32x32x16_bf16 v[80:95], v[240:243], v[100:103], v[80:95]
	s_waitcnt lgkmcnt(2)
	v_mfma_f32_32x32x16_bf16 v[64:79], v[244:247], v[100:103], v[64:79]
	v_cvt_pk_bf16_f32 v160, v160, v175
	v_cvt_pk_bf16_f32 v161, v161, v174
	v_cvt_pk_bf16_f32 v162, v162, v173
	v_cvt_pk_bf16_f32 v163, v163, v172
	v_cvt_pk_bf16_f32 v164, v164, v171
	v_cvt_pk_bf16_f32 v165, v165, v170
	s_waitcnt lgkmcnt(1)
	v_mfma_f32_32x32x16_bf16 v[80:95], v[228:231], v[96:99], v[80:95]
	s_add_i32 s50, s50, 2
	s_cmp_ge_u32 s50, s49
	s_cselect_b64 s[44:45], -1, 0
	s_and_b64 vcc, exec, s[44:45]
	s_cbranch_vccnz .Lattn_skip_loads
	v_cvt_pk_bf16_f32 v166, v166, v169
	global_load_dwordx4 v[128:131], v176, s[52:53]
	v_cvt_pk_bf16_f32 v167, v167, v168
	v_cvt_pk_bf16_f32 v168, v194, v195
	global_load_dwordx4 v[132:135], v176, s[52:53] offset:-512
	s_add_u32 s40, s52, 0x18000
	s_addc_u32 s41, s53, 0
	v_cvt_pk_bf16_f32 v169, v196, v197
	v_cvt_pk_bf16_f32 v170, v216, v209
	global_load_dwordx4 v[136:139], v176, s[40:41]
	v_cvt_pk_bf16_f32 v171, v210, v211
	v_cvt_pk_bf16_f32 v172, v212, v213
	s_waitcnt lgkmcnt(0)
	v_mfma_f32_32x32x16_bf16 v[64:79], v[232:235], v[96:99], v[64:79]
	global_load_dwordx4 v[140:143], v176, s[40:41] offset:-512
	v_cvt_pk_bf16_f32 v173, v214, v215
	v_cvt_pk_bf16_f32 v174, v217, v218
	v_cvt_pk_bf16_f32 v175, v219, v221
	s_add_u32 s52, s52, 0x30000
	s_addc_u32 s53, s53, 0

; #define SBAR() __builtin_amdgcn_sched_barrier(0)
; #define SLOAD(i, k0) do { sr_[i].vs0 = St::ld8(&Vh[(long)((k0) + sr) * LDK + sc]); sr_[i].vs1 = St::ld8(&Vh[(long)((k0) + 32 + sr) * LDK + sc]); \
;     sr_[i].ks0 = St::ld8(&Kh[(long)((k0) + sr) * LDK + sc]); sr_[i].ks1 = St::ld8(&Kh[(long)((k0) + 32 + sr) * LDK + sc]); } while (0)
; template <typename TQ>
; __device__ __forceinline__ void attn_dense_body(const TQ* __restrict__ Qb, const bf16* __restrict__ Kh, const bf16* __restrict__ Vh,
;                                                 unsigned short* __restrict__ Ob, int seq, char* lds, const int wave_s) {
;     ...
;     finishSM(pB0, pB1, alB, l_reg, pa0, pa1, pa2, pa3); SBAR();
;     if (SDEPTH == 1 || j + 3 < NT) SLOAD(SE, (j + 1 + SDEPTH) * KVBLK); SBAR();
.Lattn_skip_loads:
	s_waitcnt vmcnt(0)
	v_cvt_pk_bf16_f32 v166, v166, v169
	v_cvt_pk_bf16_f32 v167, v167, v168
	v_cvt_pk_bf16_f32 v168, v194, v195
	v_cvt_pk_bf16_f32 v169, v196, v197
	v_cvt_pk_bf16_f32 v170, v216, v209
	v_cvt_pk_bf16_f32 v171, v210, v211
	v_cvt_pk_bf16_f32 v172, v212, v213
	s_waitcnt lgkmcnt(0)
	v_mfma_f32_32x32x16_bf16 v[64:79], v[232:235], v[96:99], v[64:79]
	v_cvt_pk_bf16_f32 v173, v214, v215
	v_cvt_pk_bf16_f32 v174, v217, v218
	v_cvt_pk_bf16_f32 v175, v219, v221
	s_branch .LBB0_581
